# v150 with the phase-0 x->bf16 loop prefetching two rows ahead (three register sets, counted vmcnt 8/13/18)
# baseline (speedup 1.0000x reference)
.LBB0_54:
	s_or_b64 exec, exec, s[0:1]
	v_ashrrev_i32_e32 v87, 6, v22
	s_lshl_b32 s0, s24, 3
	v_writelane_b32 v253, s0, 4
	v_add_u32_e32 v0, s0, v87
	s_load_dword s0, s[60:61], 0x6c0
	v_and_b32_e32 v14, 63, v22
	v_mbcnt_lo_u32_b32 v52, -1, 0
	s_waitcnt lgkmcnt(0)
	s_lshl_b32 s28, s0, 3
	s_mov_b32 s0, 0x8000
	v_cmp_gt_i32_e32 vcc, s0, v0
	s_and_saveexec_b64 s[0:1], vcc
	s_cbranch_execz .LBB0_59
	v_mbcnt_hi_u32_b32 v1, -1, v52
	v_and_b32_e32 v2, 64, v1
	v_add_u32_e32 v2, 64, v2
	v_xor_b32_e32 v3, 1, v1
	v_cmp_lt_i32_e32 vcc, v3, v2
	s_load_dwordx2 s[10:11], s[60:61], 0x0
	s_mov_b64 s[2:3], 0x1f400000
	v_cndmask_b32_e32 v3, v1, v3, vcc
	v_lshlrev_b32_e32 v12, 2, v3
	v_xor_b32_e32 v3, 2, v1
	v_cmp_lt_i32_e32 vcc, v3, v2
	s_ashr_i32 s29, s28, 31
	v_cmp_gt_u32_e64 s[4:5], 4, v14
	v_cndmask_b32_e32 v3, v1, v3, vcc
	v_lshlrev_b32_e32 v13, 2, v3
	v_xor_b32_e32 v3, 4, v1
	v_cmp_lt_i32_e32 vcc, v3, v2
	v_cmp_eq_u32_e64 s[6:7], 0, v14
	s_lshl_b64 s[8:9], s[28:29], 11
	v_cndmask_b32_e32 v3, v1, v3, vcc
	v_lshlrev_b32_e32 v15, 2, v3
	v_xor_b32_e32 v3, 8, v1
	v_cmp_lt_i32_e32 vcc, v3, v2
	s_mov_b64 s[12:13], 0
	s_mov_b32 s16, 0x7000000
	v_cndmask_b32_e32 v3, v1, v3, vcc
	v_lshlrev_b32_e32 v16, 2, v3
	v_xor_b32_e32 v3, 16, v1
	v_cmp_lt_i32_e32 vcc, v3, v2
	s_movk_i32 s17, 0x7fff
	s_nop 0
	v_cndmask_b32_e32 v3, v1, v3, vcc
	v_lshlrev_b32_e32 v17, 2, v3
	v_xor_b32_e32 v3, 32, v1
	v_cmp_lt_i32_e32 vcc, v3, v2
	v_lshlrev_b32_e32 v2, 2, v14
	s_nop 0
	v_cndmask_b32_e32 v1, v1, v3, vcc
	v_lshlrev_b32_e32 v18, 2, v1
	v_ashrrev_i32_e32 v1, 31, v0
	v_lshlrev_b64 v[10:11], 12, v[0:1]
	v_mov_b32_e32 v3, 0
	v_lshl_or_b32 v10, v14, 4, v10
	v_lshl_add_u64 v[2:3], v[0:1], 4, v[2:3]
	v_lshlrev_b64 v[4:5], 11, v[0:1]
	s_waitcnt lgkmcnt(0)
	v_lshl_add_u64 v[10:11], s[10:11], 0, v[10:11]
	s_mov_b64 s[10:11], 0xc00
	v_lshl_add_u64 v[2:3], v[2:3], 0, s[2:3]
	s_lshl_b64 s[2:3], s[28:29], 4
	v_lshl_or_b32 v4, v14, 3, v4
	v_lshl_add_u64 v[10:11], v[10:11], 0, s[10:11]
	s_lshl_b64 s[10:11], s[28:29], 12
	v_mov_b32_e32 v1, v0
	global_load_dwordx4 v[24:27], v[10:11], off offset:-3072 nt
	global_load_dwordx4 v[28:31], v[10:11], off offset:-2048 nt
	global_load_dwordx4 v[32:35], v[10:11], off offset:-1024 nt
	global_load_dwordx4 v[36:39], v[10:11], off nt
	v_add_u32_e32 v1, s28, v1
	v_lshl_add_u64 v[10:11], v[10:11], 0, s[10:11]
	v_cmp_lt_i32_e32 vcc, s17, v1
	s_cbranch_vccnz .Lxb_Ta
	global_load_dwordx4 v[56:59], v[10:11], off offset:-3072 nt
	global_load_dwordx4 v[60:63], v[10:11], off offset:-2048 nt
	global_load_dwordx4 v[64:67], v[10:11], off offset:-1024 nt
	global_load_dwordx4 v[68:71], v[10:11], off nt
	v_add_u32_e32 v1, s28, v1
	v_lshl_add_u64 v[10:11], v[10:11], 0, s[10:11]
	v_cmp_lt_i32_e32 vcc, s17, v1
	s_cbranch_vccnz .Lxb_Tb
	global_load_dwordx4 v[76:79], v[10:11], off offset:-3072 nt
	global_load_dwordx4 v[80:83], v[10:11], off offset:-2048 nt
	global_load_dwordx4 v[84:87], v[10:11], off offset:-1024 nt
	global_load_dwordx4 v[88:91], v[10:11], off nt
	s_waitcnt vmcnt(8)
	v_lshl_add_u64 v[20:21], v[6:7], 0, v[4:5]
	v_add_co_u32_e32 v40, vcc, s16, v20
	s_nop 0
	v_addc_co_u32_e32 v41, vcc, 0, v21, vcc
	v_mul_f32_e32 v19, v25, v25
	v_fmac_f32_e32 v19, v24, v24
	v_mul_f32_e32 v20, v27, v27
	v_fmac_f32_e32 v20, v26, v26
	v_add_f32_e32 v19, v19, v20
	v_mul_f32_e32 v20, v29, v29
	v_mul_f32_e32 v21, v31, v31
	v_fmac_f32_e32 v20, v28, v28
	v_fmac_f32_e32 v21, v30, v30
	v_add_f32_e32 v20, v20, v21
	v_add_f32_e32 v19, v19, v20
	v_mul_f32_e32 v20, v33, v33
	v_mul_f32_e32 v21, v35, v35
	v_fmac_f32_e32 v20, v32, v32
	v_fmac_f32_e32 v21, v34, v34
	v_add_f32_e32 v20, v20, v21
	v_add_f32_e32 v19, v19, v20
	v_mul_f32_e32 v20, v37, v37
	v_mul_f32_e32 v21, v39, v39
	v_fmac_f32_e32 v20, v36, v36
	v_fmac_f32_e32 v21, v38, v38
	v_add_f32_e32 v20, v20, v21
	v_add_f32_e32 v19, v19, v20
	ds_bpermute_b32 v20, v12, v19
	v_cvt_pk_bf16_f32 v24, v24, v25
	v_cvt_pk_bf16_f32 v25, v26, v27
	global_store_dwordx2 v[40:41], v[24:25], off
	v_cvt_pk_bf16_f32 v28, v28, v29
	v_cvt_pk_bf16_f32 v29, v30, v31
	global_store_dwordx2 v[40:41], v[28:29], off offset:512
	v_cvt_pk_bf16_f32 v32, v32, v33
	v_cvt_pk_bf16_f32 v33, v34, v35
	global_store_dwordx2 v[40:41], v[32:33], off offset:1024
	v_cvt_pk_bf16_f32 v36, v36, v37
	v_cvt_pk_bf16_f32 v37, v38, v39
	global_store_dwordx2 v[40:41], v[36:37], off offset:1536
	s_waitcnt lgkmcnt(0)
	v_add_f32_e32 v19, v19, v20
	ds_bpermute_b32 v20, v13, v19
	s_waitcnt lgkmcnt(0)
	v_add_f32_e32 v19, v19, v20
	ds_bpermute_b32 v20, v15, v19
	s_waitcnt lgkmcnt(0)
	v_add_f32_e32 v19, v19, v20
	ds_bpermute_b32 v20, v16, v19
	s_waitcnt lgkmcnt(0)
	v_add_f32_e32 v19, v19, v20
	ds_bpermute_b32 v20, v17, v19
	s_waitcnt lgkmcnt(0)
	v_add_f32_e32 v19, v19, v20
	ds_bpermute_b32 v20, v18, v19
	v_lshl_add_u64 v[4:5], v[4:5], 0, s[8:9]
	s_and_saveexec_b64 s[14:15], s[4:5]
	s_waitcnt lgkmcnt(0)
	v_add_f32_e32 v19, v19, v20
	v_lshl_add_u64 v[20:21], v[6:7], 0, v[2:3]
	v_cndmask_b32_e64 v19, 0, v19, s[6:7]
	s_nop 0
	global_store_dword v[20:21], v19, off
	s_or_b64 exec, exec, s[14:15]
	v_lshl_add_u64 v[2:3], v[2:3], 0, s[2:3]
	v_add_u32_e32 v1, s28, v1
	v_lshl_add_u64 v[10:11], v[10:11], 0, s[10:11]
	v_cmp_lt_i32_e32 vcc, s17, v1
	s_cbranch_vccnz .Lxb_Tc
	global_load_dwordx4 v[24:27], v[10:11], off offset:-3072 nt
	global_load_dwordx4 v[28:31], v[10:11], off offset:-2048 nt
	global_load_dwordx4 v[32:35], v[10:11], off offset:-1024 nt
	global_load_dwordx4 v[36:39], v[10:11], off nt
	s_waitcnt vmcnt(13)
	v_lshl_add_u64 v[20:21], v[6:7], 0, v[4:5]
	v_add_co_u32_e32 v40, vcc, s16, v20
	s_nop 0
	v_addc_co_u32_e32 v41, vcc, 0, v21, vcc
	v_mul_f32_e32 v19, v57, v57
	v_fmac_f32_e32 v19, v56, v56
	v_mul_f32_e32 v20, v59, v59
	v_fmac_f32_e32 v20, v58, v58
	v_add_f32_e32 v19, v19, v20
	v_mul_f32_e32 v20, v61, v61
	v_mul_f32_e32 v21, v63, v63
	v_fmac_f32_e32 v20, v60, v60
	v_fmac_f32_e32 v21, v62, v62
	v_add_f32_e32 v20, v20, v21
	v_add_f32_e32 v19, v19, v20
	v_mul_f32_e32 v20, v65, v65
	v_mul_f32_e32 v21, v67, v67
	v_fmac_f32_e32 v20, v64, v64
	v_fmac_f32_e32 v21, v66, v66
	v_add_f32_e32 v20, v20, v21
	v_add_f32_e32 v19, v19, v20
	v_mul_f32_e32 v20, v69, v69
	v_mul_f32_e32 v21, v71, v71
	v_fmac_f32_e32 v20, v68, v68
	v_fmac_f32_e32 v21, v70, v70
	v_add_f32_e32 v20, v20, v21
	v_add_f32_e32 v19, v19, v20
	ds_bpermute_b32 v20, v12, v19
	v_cvt_pk_bf16_f32 v56, v56, v57
	v_cvt_pk_bf16_f32 v57, v58, v59
	global_store_dwordx2 v[40:41], v[56:57], off
	v_cvt_pk_bf16_f32 v60, v60, v61
	v_cvt_pk_bf16_f32 v61, v62, v63
	global_store_dwordx2 v[40:41], v[60:61], off offset:512
	v_cvt_pk_bf16_f32 v64, v64, v65
	v_cvt_pk_bf16_f32 v65, v66, v67
	global_store_dwordx2 v[40:41], v[64:65], off offset:1024
	v_cvt_pk_bf16_f32 v68, v68, v69
	v_cvt_pk_bf16_f32 v69, v70, v71
	global_store_dwordx2 v[40:41], v[68:69], off offset:1536
	s_waitcnt lgkmcnt(0)
	v_add_f32_e32 v19, v19, v20
	ds_bpermute_b32 v20, v13, v19
	s_waitcnt lgkmcnt(0)
	v_add_f32_e32 v19, v19, v20
	ds_bpermute_b32 v20, v15, v19
	s_waitcnt lgkmcnt(0)
	v_add_f32_e32 v19, v19, v20
	ds_bpermute_b32 v20, v16, v19
	s_waitcnt lgkmcnt(0)
	v_add_f32_e32 v19, v19, v20
	ds_bpermute_b32 v20, v17, v19
	s_waitcnt lgkmcnt(0)
	v_add_f32_e32 v19, v19, v20
	ds_bpermute_b32 v20, v18, v19
	v_lshl_add_u64 v[4:5], v[4:5], 0, s[8:9]
	s_and_saveexec_b64 s[14:15], s[4:5]
	s_waitcnt lgkmcnt(0)
	v_add_f32_e32 v19, v19, v20
	v_lshl_add_u64 v[20:21], v[6:7], 0, v[2:3]
	v_cndmask_b32_e64 v19, 0, v19, s[6:7]
	s_nop 0
	global_store_dword v[20:21], v19, off
	s_or_b64 exec, exec, s[14:15]
	v_lshl_add_u64 v[2:3], v[2:3], 0, s[2:3]
.Lxb_loop:
	v_add_u32_e32 v1, s28, v1
	v_lshl_add_u64 v[10:11], v[10:11], 0, s[10:11]
	v_cmp_lt_i32_e32 vcc, s17, v1
	s_cbranch_vccnz .Lxb_T2
	global_load_dwordx4 v[56:59], v[10:11], off offset:-3072 nt
	global_load_dwordx4 v[60:63], v[10:11], off offset:-2048 nt
	global_load_dwordx4 v[64:67], v[10:11], off offset:-1024 nt
	global_load_dwordx4 v[68:71], v[10:11], off nt
	s_waitcnt vmcnt(18)
	v_lshl_add_u64 v[20:21], v[6:7], 0, v[4:5]
	v_add_co_u32_e32 v40, vcc, s16, v20
	s_nop 0
	v_addc_co_u32_e32 v41, vcc, 0, v21, vcc
	v_mul_f32_e32 v19, v77, v77
	v_fmac_f32_e32 v19, v76, v76
	v_mul_f32_e32 v20, v79, v79
	v_fmac_f32_e32 v20, v78, v78
	v_add_f32_e32 v19, v19, v20
	v_mul_f32_e32 v20, v81, v81
	v_mul_f32_e32 v21, v83, v83
	v_fmac_f32_e32 v20, v80, v80
	v_fmac_f32_e32 v21, v82, v82
	v_add_f32_e32 v20, v20, v21
	v_add_f32_e32 v19, v19, v20
	v_mul_f32_e32 v20, v85, v85
	v_mul_f32_e32 v21, v87, v87
	v_fmac_f32_e32 v20, v84, v84
	v_fmac_f32_e32 v21, v86, v86
	v_add_f32_e32 v20, v20, v21
	v_add_f32_e32 v19, v19, v20
	v_mul_f32_e32 v20, v89, v89
	v_mul_f32_e32 v21, v91, v91
	v_fmac_f32_e32 v20, v88, v88
	v_fmac_f32_e32 v21, v90, v90
	v_add_f32_e32 v20, v20, v21
	v_add_f32_e32 v19, v19, v20
	ds_bpermute_b32 v20, v12, v19
	v_cvt_pk_bf16_f32 v76, v76, v77
	v_cvt_pk_bf16_f32 v77, v78, v79
	global_store_dwordx2 v[40:41], v[76:77], off
	v_cvt_pk_bf16_f32 v80, v80, v81
	v_cvt_pk_bf16_f32 v81, v82, v83
	global_store_dwordx2 v[40:41], v[80:81], off offset:512
	v_cvt_pk_bf16_f32 v84, v84, v85
	v_cvt_pk_bf16_f32 v85, v86, v87
	global_store_dwordx2 v[40:41], v[84:85], off offset:1024
	v_cvt_pk_bf16_f32 v88, v88, v89
	v_cvt_pk_bf16_f32 v89, v90, v91
	global_store_dwordx2 v[40:41], v[88:89], off offset:1536
	s_waitcnt lgkmcnt(0)
	v_add_f32_e32 v19, v19, v20
	ds_bpermute_b32 v20, v13, v19
	s_waitcnt lgkmcnt(0)
	v_add_f32_e32 v19, v19, v20
	ds_bpermute_b32 v20, v15, v19
	s_waitcnt lgkmcnt(0)
	v_add_f32_e32 v19, v19, v20
	ds_bpermute_b32 v20, v16, v19
	s_waitcnt lgkmcnt(0)
	v_add_f32_e32 v19, v19, v20
	ds_bpermute_b32 v20, v17, v19
	s_waitcnt lgkmcnt(0)
	v_add_f32_e32 v19, v19, v20
	ds_bpermute_b32 v20, v18, v19
	v_lshl_add_u64 v[4:5], v[4:5], 0, s[8:9]
	s_and_saveexec_b64 s[14:15], s[4:5]
	s_waitcnt lgkmcnt(0)
	v_add_f32_e32 v19, v19, v20
	v_lshl_add_u64 v[20:21], v[6:7], 0, v[2:3]
	v_cndmask_b32_e64 v19, 0, v19, s[6:7]
	s_nop 0
	global_store_dword v[20:21], v19, off
	s_or_b64 exec, exec, s[14:15]
	v_lshl_add_u64 v[2:3], v[2:3], 0, s[2:3]
	v_add_u32_e32 v1, s28, v1
	v_lshl_add_u64 v[10:11], v[10:11], 0, s[10:11]
	v_cmp_lt_i32_e32 vcc, s17, v1
	s_cbranch_vccnz .Lxb_T0
	global_load_dwordx4 v[76:79], v[10:11], off offset:-3072 nt
	global_load_dwordx4 v[80:83], v[10:11], off offset:-2048 nt
	global_load_dwordx4 v[84:87], v[10:11], off offset:-1024 nt
	global_load_dwordx4 v[88:91], v[10:11], off nt
	s_waitcnt vmcnt(18)
	v_lshl_add_u64 v[20:21], v[6:7], 0, v[4:5]
	v_add_co_u32_e32 v40, vcc, s16, v20
	s_nop 0
	v_addc_co_u32_e32 v41, vcc, 0, v21, vcc
	v_mul_f32_e32 v19, v25, v25
	v_fmac_f32_e32 v19, v24, v24
	v_mul_f32_e32 v20, v27, v27
	v_fmac_f32_e32 v20, v26, v26
	v_add_f32_e32 v19, v19, v20
	v_mul_f32_e32 v20, v29, v29
	v_mul_f32_e32 v21, v31, v31
	v_fmac_f32_e32 v20, v28, v28
	v_fmac_f32_e32 v21, v30, v30
	v_add_f32_e32 v20, v20, v21
	v_add_f32_e32 v19, v19, v20
	v_mul_f32_e32 v20, v33, v33
	v_mul_f32_e32 v21, v35, v35
	v_fmac_f32_e32 v20, v32, v32
	v_fmac_f32_e32 v21, v34, v34
	v_add_f32_e32 v20, v20, v21
	v_add_f32_e32 v19, v19, v20
	v_mul_f32_e32 v20, v37, v37
	v_mul_f32_e32 v21, v39, v39
	v_fmac_f32_e32 v20, v36, v36
	v_fmac_f32_e32 v21, v38, v38
	v_add_f32_e32 v20, v20, v21
	v_add_f32_e32 v19, v19, v20
	ds_bpermute_b32 v20, v12, v19
	v_cvt_pk_bf16_f32 v24, v24, v25
	v_cvt_pk_bf16_f32 v25, v26, v27
	global_store_dwordx2 v[40:41], v[24:25], off
	v_cvt_pk_bf16_f32 v28, v28, v29
	v_cvt_pk_bf16_f32 v29, v30, v31
	global_store_dwordx2 v[40:41], v[28:29], off offset:512
	v_cvt_pk_bf16_f32 v32, v32, v33
	v_cvt_pk_bf16_f32 v33, v34, v35
	global_store_dwordx2 v[40:41], v[32:33], off offset:1024
	v_cvt_pk_bf16_f32 v36, v36, v37
	v_cvt_pk_bf16_f32 v37, v38, v39
	global_store_dwordx2 v[40:41], v[36:37], off offset:1536
	s_waitcnt lgkmcnt(0)
	v_add_f32_e32 v19, v19, v20
	ds_bpermute_b32 v20, v13, v19
	s_waitcnt lgkmcnt(0)
	v_add_f32_e32 v19, v19, v20
	ds_bpermute_b32 v20, v15, v19
	s_waitcnt lgkmcnt(0)
	v_add_f32_e32 v19, v19, v20
	ds_bpermute_b32 v20, v16, v19
	s_waitcnt lgkmcnt(0)
	v_add_f32_e32 v19, v19, v20
	ds_bpermute_b32 v20, v17, v19
	s_waitcnt lgkmcnt(0)
	v_add_f32_e32 v19, v19, v20
	ds_bpermute_b32 v20, v18, v19
	v_lshl_add_u64 v[4:5], v[4:5], 0, s[8:9]
	s_and_saveexec_b64 s[14:15], s[4:5]
	s_waitcnt lgkmcnt(0)
	v_add_f32_e32 v19, v19, v20
	v_lshl_add_u64 v[20:21], v[6:7], 0, v[2:3]
	v_cndmask_b32_e64 v19, 0, v19, s[6:7]
	s_nop 0
	global_store_dword v[20:21], v19, off
	s_or_b64 exec, exec, s[14:15]
	v_lshl_add_u64 v[2:3], v[2:3], 0, s[2:3]
	v_add_u32_e32 v1, s28, v1
	v_lshl_add_u64 v[10:11], v[10:11], 0, s[10:11]
	v_cmp_lt_i32_e32 vcc, s17, v1
	s_cbranch_vccnz .Lxb_T1
	global_load_dwordx4 v[24:27], v[10:11], off offset:-3072 nt
	global_load_dwordx4 v[28:31], v[10:11], off offset:-2048 nt
	global_load_dwordx4 v[32:35], v[10:11], off offset:-1024 nt
	global_load_dwordx4 v[36:39], v[10:11], off nt
	s_waitcnt vmcnt(18)
	v_lshl_add_u64 v[20:21], v[6:7], 0, v[4:5]
	v_add_co_u32_e32 v40, vcc, s16, v20
	s_nop 0
	v_addc_co_u32_e32 v41, vcc, 0, v21, vcc
	v_mul_f32_e32 v19, v57, v57
	v_fmac_f32_e32 v19, v56, v56
	v_mul_f32_e32 v20, v59, v59
	v_fmac_f32_e32 v20, v58, v58
	v_add_f32_e32 v19, v19, v20
	v_mul_f32_e32 v20, v61, v61
	v_mul_f32_e32 v21, v63, v63
	v_fmac_f32_e32 v20, v60, v60
	v_fmac_f32_e32 v21, v62, v62
	v_add_f32_e32 v20, v20, v21
	v_add_f32_e32 v19, v19, v20
	v_mul_f32_e32 v20, v65, v65
	v_mul_f32_e32 v21, v67, v67
	v_fmac_f32_e32 v20, v64, v64
	v_fmac_f32_e32 v21, v66, v66
	v_add_f32_e32 v20, v20, v21
	v_add_f32_e32 v19, v19, v20
	v_mul_f32_e32 v20, v69, v69
	v_mul_f32_e32 v21, v71, v71
	v_fmac_f32_e32 v20, v68, v68
	v_fmac_f32_e32 v21, v70, v70
	v_add_f32_e32 v20, v20, v21
	v_add_f32_e32 v19, v19, v20
	ds_bpermute_b32 v20, v12, v19
	v_cvt_pk_bf16_f32 v56, v56, v57
	v_cvt_pk_bf16_f32 v57, v58, v59
	global_store_dwordx2 v[40:41], v[56:57], off
	v_cvt_pk_bf16_f32 v60, v60, v61
	v_cvt_pk_bf16_f32 v61, v62, v63
	global_store_dwordx2 v[40:41], v[60:61], off offset:512
	v_cvt_pk_bf16_f32 v64, v64, v65
	v_cvt_pk_bf16_f32 v65, v66, v67
	global_store_dwordx2 v[40:41], v[64:65], off offset:1024
	v_cvt_pk_bf16_f32 v68, v68, v69
	v_cvt_pk_bf16_f32 v69, v70, v71
	global_store_dwordx2 v[40:41], v[68:69], off offset:1536
	s_waitcnt lgkmcnt(0)
	v_add_f32_e32 v19, v19, v20
	ds_bpermute_b32 v20, v13, v19
	s_waitcnt lgkmcnt(0)
	v_add_f32_e32 v19, v19, v20
	ds_bpermute_b32 v20, v15, v19
	s_waitcnt lgkmcnt(0)
	v_add_f32_e32 v19, v19, v20
	ds_bpermute_b32 v20, v16, v19
	s_waitcnt lgkmcnt(0)
	v_add_f32_e32 v19, v19, v20
	ds_bpermute_b32 v20, v17, v19
	s_waitcnt lgkmcnt(0)
	v_add_f32_e32 v19, v19, v20
	ds_bpermute_b32 v20, v18, v19
	v_lshl_add_u64 v[4:5], v[4:5], 0, s[8:9]
	s_and_saveexec_b64 s[14:15], s[4:5]
	s_waitcnt lgkmcnt(0)
	v_add_f32_e32 v19, v19, v20
	v_lshl_add_u64 v[20:21], v[6:7], 0, v[2:3]
	v_cndmask_b32_e64 v19, 0, v19, s[6:7]
	s_nop 0
	global_store_dword v[20:21], v19, off
	s_or_b64 exec, exec, s[14:15]
	v_lshl_add_u64 v[2:3], v[2:3], 0, s[2:3]
	s_branch .Lxb_loop

.Lxb_Tb:
	s_waitcnt vmcnt(0)
	v_lshl_add_u64 v[20:21], v[6:7], 0, v[4:5]
	v_add_co_u32_e32 v40, vcc, s16, v20
	s_nop 0
	v_addc_co_u32_e32 v41, vcc, 0, v21, vcc
	v_mul_f32_e32 v19, v25, v25
	v_fmac_f32_e32 v19, v24, v24
	v_mul_f32_e32 v20, v27, v27
	v_fmac_f32_e32 v20, v26, v26
	v_add_f32_e32 v19, v19, v20
	v_mul_f32_e32 v20, v29, v29
	v_mul_f32_e32 v21, v31, v31
	v_fmac_f32_e32 v20, v28, v28
	v_fmac_f32_e32 v21, v30, v30
	v_add_f32_e32 v20, v20, v21
	v_add_f32_e32 v19, v19, v20
	v_mul_f32_e32 v20, v33, v33
	v_mul_f32_e32 v21, v35, v35
	v_fmac_f32_e32 v20, v32, v32
	v_fmac_f32_e32 v21, v34, v34
	v_add_f32_e32 v20, v20, v21
	v_add_f32_e32 v19, v19, v20
	v_mul_f32_e32 v20, v37, v37
	v_mul_f32_e32 v21, v39, v39
	v_fmac_f32_e32 v20, v36, v36
	v_fmac_f32_e32 v21, v38, v38
	v_add_f32_e32 v20, v20, v21
	v_add_f32_e32 v19, v19, v20
	ds_bpermute_b32 v20, v12, v19
	v_cvt_pk_bf16_f32 v24, v24, v25
	v_cvt_pk_bf16_f32 v25, v26, v27
	global_store_dwordx2 v[40:41], v[24:25], off
	v_cvt_pk_bf16_f32 v28, v28, v29
	v_cvt_pk_bf16_f32 v29, v30, v31
	global_store_dwordx2 v[40:41], v[28:29], off offset:512
	v_cvt_pk_bf16_f32 v32, v32, v33
	v_cvt_pk_bf16_f32 v33, v34, v35
	global_store_dwordx2 v[40:41], v[32:33], off offset:1024
	v_cvt_pk_bf16_f32 v36, v36, v37
	v_cvt_pk_bf16_f32 v37, v38, v39
	global_store_dwordx2 v[40:41], v[36:37], off offset:1536
	s_waitcnt lgkmcnt(0)
	v_add_f32_e32 v19, v19, v20
	ds_bpermute_b32 v20, v13, v19
	s_waitcnt lgkmcnt(0)
	v_add_f32_e32 v19, v19, v20
	ds_bpermute_b32 v20, v15, v19
	s_waitcnt lgkmcnt(0)
	v_add_f32_e32 v19, v19, v20
	ds_bpermute_b32 v20, v16, v19
	s_waitcnt lgkmcnt(0)
	v_add_f32_e32 v19, v19, v20
	ds_bpermute_b32 v20, v17, v19
	s_waitcnt lgkmcnt(0)
	v_add_f32_e32 v19, v19, v20
	ds_bpermute_b32 v20, v18, v19
	v_lshl_add_u64 v[4:5], v[4:5], 0, s[8:9]
	s_and_saveexec_b64 s[14:15], s[4:5]
	s_waitcnt lgkmcnt(0)
	v_add_f32_e32 v19, v19, v20
	v_lshl_add_u64 v[20:21], v[6:7], 0, v[2:3]
	v_cndmask_b32_e64 v19, 0, v19, s[6:7]
	s_nop 0
	global_store_dword v[20:21], v19, off
	s_or_b64 exec, exec, s[14:15]
	v_lshl_add_u64 v[2:3], v[2:3], 0, s[2:3]
	v_lshl_add_u64 v[20:21], v[6:7], 0, v[4:5]
	v_add_co_u32_e32 v40, vcc, s16, v20
	s_nop 0
	v_addc_co_u32_e32 v41, vcc, 0, v21, vcc
	v_mul_f32_e32 v19, v57, v57
	v_fmac_f32_e32 v19, v56, v56
	v_mul_f32_e32 v20, v59, v59
	v_fmac_f32_e32 v20, v58, v58
	v_add_f32_e32 v19, v19, v20
	v_mul_f32_e32 v20, v61, v61
	v_mul_f32_e32 v21, v63, v63
	v_fmac_f32_e32 v20, v60, v60
	v_fmac_f32_e32 v21, v62, v62
	v_add_f32_e32 v20, v20, v21
	v_add_f32_e32 v19, v19, v20
	v_mul_f32_e32 v20, v65, v65
	v_mul_f32_e32 v21, v67, v67
	v_fmac_f32_e32 v20, v64, v64
	v_fmac_f32_e32 v21, v66, v66
	v_add_f32_e32 v20, v20, v21
	v_add_f32_e32 v19, v19, v20
	v_mul_f32_e32 v20, v69, v69
	v_mul_f32_e32 v21, v71, v71
	v_fmac_f32_e32 v20, v68, v68
	v_fmac_f32_e32 v21, v70, v70
	v_add_f32_e32 v20, v20, v21
	v_add_f32_e32 v19, v19, v20
	ds_bpermute_b32 v20, v12, v19
	v_cvt_pk_bf16_f32 v56, v56, v57
	v_cvt_pk_bf16_f32 v57, v58, v59
	global_store_dwordx2 v[40:41], v[56:57], off
	v_cvt_pk_bf16_f32 v60, v60, v61
	v_cvt_pk_bf16_f32 v61, v62, v63
	global_store_dwordx2 v[40:41], v[60:61], off offset:512
	v_cvt_pk_bf16_f32 v64, v64, v65
	v_cvt_pk_bf16_f32 v65, v66, v67
	global_store_dwordx2 v[40:41], v[64:65], off offset:1024
	v_cvt_pk_bf16_f32 v68, v68, v69
	v_cvt_pk_bf16_f32 v69, v70, v71
	global_store_dwordx2 v[40:41], v[68:69], off offset:1536
	s_waitcnt lgkmcnt(0)
	v_add_f32_e32 v19, v19, v20
	ds_bpermute_b32 v20, v13, v19
	s_waitcnt lgkmcnt(0)
	v_add_f32_e32 v19, v19, v20
	ds_bpermute_b32 v20, v15, v19
	s_waitcnt lgkmcnt(0)
	v_add_f32_e32 v19, v19, v20
	ds_bpermute_b32 v20, v16, v19
	s_waitcnt lgkmcnt(0)
	v_add_f32_e32 v19, v19, v20
	ds_bpermute_b32 v20, v17, v19
	s_waitcnt lgkmcnt(0)
	v_add_f32_e32 v19, v19, v20
	ds_bpermute_b32 v20, v18, v19
	v_lshl_add_u64 v[4:5], v[4:5], 0, s[8:9]
	s_and_saveexec_b64 s[14:15], s[4:5]
	s_waitcnt lgkmcnt(0)
	v_add_f32_e32 v19, v19, v20
	v_lshl_add_u64 v[20:21], v[6:7], 0, v[2:3]
	v_cndmask_b32_e64 v19, 0, v19, s[6:7]
	s_nop 0
	global_store_dword v[20:21], v19, off
	s_or_b64 exec, exec, s[14:15]
	v_lshl_add_u64 v[2:3], v[2:3], 0, s[2:3]
	s_branch .Lxb_end
.Lxb_Tc:
	s_waitcnt vmcnt(0)
	v_lshl_add_u64 v[20:21], v[6:7], 0, v[4:5]
	v_add_co_u32_e32 v40, vcc, s16, v20
	s_nop 0
	v_addc_co_u32_e32 v41, vcc, 0, v21, vcc
	v_mul_f32_e32 v19, v57, v57
	v_fmac_f32_e32 v19, v56, v56
	v_mul_f32_e32 v20, v59, v59
	v_fmac_f32_e32 v20, v58, v58
	v_add_f32_e32 v19, v19, v20
	v_mul_f32_e32 v20, v61, v61
	v_mul_f32_e32 v21, v63, v63
	v_fmac_f32_e32 v20, v60, v60
	v_fmac_f32_e32 v21, v62, v62
	v_add_f32_e32 v20, v20, v21
	v_add_f32_e32 v19, v19, v20
	v_mul_f32_e32 v20, v65, v65
	v_mul_f32_e32 v21, v67, v67
	v_fmac_f32_e32 v20, v64, v64
	v_fmac_f32_e32 v21, v66, v66
	v_add_f32_e32 v20, v20, v21
	v_add_f32_e32 v19, v19, v20
	v_mul_f32_e32 v20, v69, v69
	v_mul_f32_e32 v21, v71, v71
	v_fmac_f32_e32 v20, v68, v68
	v_fmac_f32_e32 v21, v70, v70
	v_add_f32_e32 v20, v20, v21
	v_add_f32_e32 v19, v19, v20
	ds_bpermute_b32 v20, v12, v19
	v_cvt_pk_bf16_f32 v56, v56, v57
	v_cvt_pk_bf16_f32 v57, v58, v59
	global_store_dwordx2 v[40:41], v[56:57], off
	v_cvt_pk_bf16_f32 v60, v60, v61
	v_cvt_pk_bf16_f32 v61, v62, v63
	global_store_dwordx2 v[40:41], v[60:61], off offset:512
	v_cvt_pk_bf16_f32 v64, v64, v65
	v_cvt_pk_bf16_f32 v65, v66, v67
	global_store_dwordx2 v[40:41], v[64:65], off offset:1024
	v_cvt_pk_bf16_f32 v68, v68, v69
	v_cvt_pk_bf16_f32 v69, v70, v71
	global_store_dwordx2 v[40:41], v[68:69], off offset:1536
	s_waitcnt lgkmcnt(0)
	v_add_f32_e32 v19, v19, v20
	ds_bpermute_b32 v20, v13, v19
	s_waitcnt lgkmcnt(0)
	v_add_f32_e32 v19, v19, v20
	ds_bpermute_b32 v20, v15, v19
	s_waitcnt lgkmcnt(0)
	v_add_f32_e32 v19, v19, v20
	ds_bpermute_b32 v20, v16, v19
	s_waitcnt lgkmcnt(0)
	v_add_f32_e32 v19, v19, v20
	ds_bpermute_b32 v20, v17, v19
	s_waitcnt lgkmcnt(0)
	v_add_f32_e32 v19, v19, v20
	ds_bpermute_b32 v20, v18, v19
	v_lshl_add_u64 v[4:5], v[4:5], 0, s[8:9]
	s_and_saveexec_b64 s[14:15], s[4:5]
	s_waitcnt lgkmcnt(0)
	v_add_f32_e32 v19, v19, v20
	v_lshl_add_u64 v[20:21], v[6:7], 0, v[2:3]
	v_cndmask_b32_e64 v19, 0, v19, s[6:7]
	s_nop 0
	global_store_dword v[20:21], v19, off
	s_or_b64 exec, exec, s[14:15]
	v_lshl_add_u64 v[2:3], v[2:3], 0, s[2:3]
	v_lshl_add_u64 v[20:21], v[6:7], 0, v[4:5]
	v_add_co_u32_e32 v40, vcc, s16, v20
	s_nop 0
	v_addc_co_u32_e32 v41, vcc, 0, v21, vcc
	v_mul_f32_e32 v19, v77, v77
	v_fmac_f32_e32 v19, v76, v76
	v_mul_f32_e32 v20, v79, v79
	v_fmac_f32_e32 v20, v78, v78
	v_add_f32_e32 v19, v19, v20
	v_mul_f32_e32 v20, v81, v81
	v_mul_f32_e32 v21, v83, v83
	v_fmac_f32_e32 v20, v80, v80
	v_fmac_f32_e32 v21, v82, v82
	v_add_f32_e32 v20, v20, v21
	v_add_f32_e32 v19, v19, v20
	v_mul_f32_e32 v20, v85, v85
	v_mul_f32_e32 v21, v87, v87
	v_fmac_f32_e32 v20, v84, v84
	v_fmac_f32_e32 v21, v86, v86
	v_add_f32_e32 v20, v20, v21
	v_add_f32_e32 v19, v19, v20
	v_mul_f32_e32 v20, v89, v89
	v_mul_f32_e32 v21, v91, v91
	v_fmac_f32_e32 v20, v88, v88
	v_fmac_f32_e32 v21, v90, v90
	v_add_f32_e32 v20, v20, v21
	v_add_f32_e32 v19, v19, v20
	ds_bpermute_b32 v20, v12, v19
	v_cvt_pk_bf16_f32 v76, v76, v77
	v_cvt_pk_bf16_f32 v77, v78, v79
	global_store_dwordx2 v[40:41], v[76:77], off
	v_cvt_pk_bf16_f32 v80, v80, v81
	v_cvt_pk_bf16_f32 v81, v82, v83
	global_store_dwordx2 v[40:41], v[80:81], off offset:512
	v_cvt_pk_bf16_f32 v84, v84, v85
	v_cvt_pk_bf16_f32 v85, v86, v87
	global_store_dwordx2 v[40:41], v[84:85], off offset:1024
	v_cvt_pk_bf16_f32 v88, v88, v89
	v_cvt_pk_bf16_f32 v89, v90, v91
	global_store_dwordx2 v[40:41], v[88:89], off offset:1536
	s_waitcnt lgkmcnt(0)
	v_add_f32_e32 v19, v19, v20
	ds_bpermute_b32 v20, v13, v19
	s_waitcnt lgkmcnt(0)
	v_add_f32_e32 v19, v19, v20
	ds_bpermute_b32 v20, v15, v19
	s_waitcnt lgkmcnt(0)
	v_add_f32_e32 v19, v19, v20
	ds_bpermute_b32 v20, v16, v19
	s_waitcnt lgkmcnt(0)
	v_add_f32_e32 v19, v19, v20
	ds_bpermute_b32 v20, v17, v19
	s_waitcnt lgkmcnt(0)
	v_add_f32_e32 v19, v19, v20
	ds_bpermute_b32 v20, v18, v19
	v_lshl_add_u64 v[4:5], v[4:5], 0, s[8:9]
	s_and_saveexec_b64 s[14:15], s[4:5]
	s_waitcnt lgkmcnt(0)
	v_add_f32_e32 v19, v19, v20
	v_lshl_add_u64 v[20:21], v[6:7], 0, v[2:3]
	v_cndmask_b32_e64 v19, 0, v19, s[6:7]
	s_nop 0
	global_store_dword v[20:21], v19, off
	s_or_b64 exec, exec, s[14:15]
	v_lshl_add_u64 v[2:3], v[2:3], 0, s[2:3]
	s_branch .Lxb_end
.Lxb_T2:
	s_waitcnt vmcnt(0)
	v_lshl_add_u64 v[20:21], v[6:7], 0, v[4:5]
	v_add_co_u32_e32 v40, vcc, s16, v20
	s_nop 0
	v_addc_co_u32_e32 v41, vcc, 0, v21, vcc
	v_mul_f32_e32 v19, v77, v77
	v_fmac_f32_e32 v19, v76, v76
	v_mul_f32_e32 v20, v79, v79
	v_fmac_f32_e32 v20, v78, v78
	v_add_f32_e32 v19, v19, v20
	v_mul_f32_e32 v20, v81, v81
	v_mul_f32_e32 v21, v83, v83
	v_fmac_f32_e32 v20, v80, v80
	v_fmac_f32_e32 v21, v82, v82
	v_add_f32_e32 v20, v20, v21
	v_add_f32_e32 v19, v19, v20
	v_mul_f32_e32 v20, v85, v85
	v_mul_f32_e32 v21, v87, v87
	v_fmac_f32_e32 v20, v84, v84
	v_fmac_f32_e32 v21, v86, v86
	v_add_f32_e32 v20, v20, v21
	v_add_f32_e32 v19, v19, v20
	v_mul_f32_e32 v20, v89, v89
	v_mul_f32_e32 v21, v91, v91
	v_fmac_f32_e32 v20, v88, v88
	v_fmac_f32_e32 v21, v90, v90
	v_add_f32_e32 v20, v20, v21
	v_add_f32_e32 v19, v19, v20
	ds_bpermute_b32 v20, v12, v19
	v_cvt_pk_bf16_f32 v76, v76, v77
	v_cvt_pk_bf16_f32 v77, v78, v79
	global_store_dwordx2 v[40:41], v[76:77], off
	v_cvt_pk_bf16_f32 v80, v80, v81
	v_cvt_pk_bf16_f32 v81, v82, v83
	global_store_dwordx2 v[40:41], v[80:81], off offset:512
	v_cvt_pk_bf16_f32 v84, v84, v85
	v_cvt_pk_bf16_f32 v85, v86, v87
	global_store_dwordx2 v[40:41], v[84:85], off offset:1024
	v_cvt_pk_bf16_f32 v88, v88, v89
	v_cvt_pk_bf16_f32 v89, v90, v91
	global_store_dwordx2 v[40:41], v[88:89], off offset:1536
	s_waitcnt lgkmcnt(0)
	v_add_f32_e32 v19, v19, v20
	ds_bpermute_b32 v20, v13, v19
	s_waitcnt lgkmcnt(0)
	v_add_f32_e32 v19, v19, v20
	ds_bpermute_b32 v20, v15, v19
	s_waitcnt lgkmcnt(0)
	v_add_f32_e32 v19, v19, v20
	ds_bpermute_b32 v20, v16, v19
	s_waitcnt lgkmcnt(0)
	v_add_f32_e32 v19, v19, v20
	ds_bpermute_b32 v20, v17, v19
	s_waitcnt lgkmcnt(0)
	v_add_f32_e32 v19, v19, v20
	ds_bpermute_b32 v20, v18, v19
	v_lshl_add_u64 v[4:5], v[4:5], 0, s[8:9]
	s_and_saveexec_b64 s[14:15], s[4:5]
	s_waitcnt lgkmcnt(0)
	v_add_f32_e32 v19, v19, v20
	v_lshl_add_u64 v[20:21], v[6:7], 0, v[2:3]
	v_cndmask_b32_e64 v19, 0, v19, s[6:7]
	s_nop 0
	global_store_dword v[20:21], v19, off
	s_or_b64 exec, exec, s[14:15]
	v_lshl_add_u64 v[2:3], v[2:3], 0, s[2:3]
	v_lshl_add_u64 v[20:21], v[6:7], 0, v[4:5]
	v_add_co_u32_e32 v40, vcc, s16, v20
	s_nop 0
	v_addc_co_u32_e32 v41, vcc, 0, v21, vcc
	v_mul_f32_e32 v19, v25, v25
	v_fmac_f32_e32 v19, v24, v24
	v_mul_f32_e32 v20, v27, v27
	v_fmac_f32_e32 v20, v26, v26
	v_add_f32_e32 v19, v19, v20
	v_mul_f32_e32 v20, v29, v29
	v_mul_f32_e32 v21, v31, v31
	v_fmac_f32_e32 v20, v28, v28
	v_fmac_f32_e32 v21, v30, v30
	v_add_f32_e32 v20, v20, v21
	v_add_f32_e32 v19, v19, v20
	v_mul_f32_e32 v20, v33, v33
	v_mul_f32_e32 v21, v35, v35
	v_fmac_f32_e32 v20, v32, v32
	v_fmac_f32_e32 v21, v34, v34
	v_add_f32_e32 v20, v20, v21
	v_add_f32_e32 v19, v19, v20
	v_mul_f32_e32 v20, v37, v37
	v_mul_f32_e32 v21, v39, v39
	v_fmac_f32_e32 v20, v36, v36
	v_fmac_f32_e32 v21, v38, v38
	v_add_f32_e32 v20, v20, v21
	v_add_f32_e32 v19, v19, v20
	ds_bpermute_b32 v20, v12, v19
	v_cvt_pk_bf16_f32 v24, v24, v25
	v_cvt_pk_bf16_f32 v25, v26, v27
	global_store_dwordx2 v[40:41], v[24:25], off
	v_cvt_pk_bf16_f32 v28, v28, v29
	v_cvt_pk_bf16_f32 v29, v30, v31
	global_store_dwordx2 v[40:41], v[28:29], off offset:512
	v_cvt_pk_bf16_f32 v32, v32, v33
	v_cvt_pk_bf16_f32 v33, v34, v35
	global_store_dwordx2 v[40:41], v[32:33], off offset:1024
	v_cvt_pk_bf16_f32 v36, v36, v37
	v_cvt_pk_bf16_f32 v37, v38, v39
	global_store_dwordx2 v[40:41], v[36:37], off offset:1536
	s_waitcnt lgkmcnt(0)
	v_add_f32_e32 v19, v19, v20
	ds_bpermute_b32 v20, v13, v19
	s_waitcnt lgkmcnt(0)
	v_add_f32_e32 v19, v19, v20
	ds_bpermute_b32 v20, v15, v19
	s_waitcnt lgkmcnt(0)
	v_add_f32_e32 v19, v19, v20
	ds_bpermute_b32 v20, v16, v19
	s_waitcnt lgkmcnt(0)
	v_add_f32_e32 v19, v19, v20
	ds_bpermute_b32 v20, v17, v19
	s_waitcnt lgkmcnt(0)
	v_add_f32_e32 v19, v19, v20
	ds_bpermute_b32 v20, v18, v19
	v_lshl_add_u64 v[4:5], v[4:5], 0, s[8:9]
	s_and_saveexec_b64 s[14:15], s[4:5]
	s_waitcnt lgkmcnt(0)
	v_add_f32_e32 v19, v19, v20
	v_lshl_add_u64 v[20:21], v[6:7], 0, v[2:3]
	v_cndmask_b32_e64 v19, 0, v19, s[6:7]
	s_nop 0
	global_store_dword v[20:21], v19, off
	s_or_b64 exec, exec, s[14:15]
	v_lshl_add_u64 v[2:3], v[2:3], 0, s[2:3]
	s_branch .Lxb_end

.Lxb_T1:
	s_waitcnt vmcnt(0)
	v_lshl_add_u64 v[20:21], v[6:7], 0, v[4:5]
	v_add_co_u32_e32 v40, vcc, s16, v20
	s_nop 0
	v_addc_co_u32_e32 v41, vcc, 0, v21, vcc
	v_mul_f32_e32 v19, v57, v57
	v_fmac_f32_e32 v19, v56, v56
	v_mul_f32_e32 v20, v59, v59
	v_fmac_f32_e32 v20, v58, v58
	v_add_f32_e32 v19, v19, v20
	v_mul_f32_e32 v20, v61, v61
	v_mul_f32_e32 v21, v63, v63
	v_fmac_f32_e32 v20, v60, v60
	v_fmac_f32_e32 v21, v62, v62
	v_add_f32_e32 v20, v20, v21
	v_add_f32_e32 v19, v19, v20
	v_mul_f32_e32 v20, v65, v65
	v_mul_f32_e32 v21, v67, v67
	v_fmac_f32_e32 v20, v64, v64
	v_fmac_f32_e32 v21, v66, v66
	v_add_f32_e32 v20, v20, v21
	v_add_f32_e32 v19, v19, v20
	v_mul_f32_e32 v20, v69, v69
	v_mul_f32_e32 v21, v71, v71
	v_fmac_f32_e32 v20, v68, v68
	v_fmac_f32_e32 v21, v70, v70
	v_add_f32_e32 v20, v20, v21
	v_add_f32_e32 v19, v19, v20
	ds_bpermute_b32 v20, v12, v19
	v_cvt_pk_bf16_f32 v56, v56, v57
	v_cvt_pk_bf16_f32 v57, v58, v59
	global_store_dwordx2 v[40:41], v[56:57], off
	v_cvt_pk_bf16_f32 v60, v60, v61
	v_cvt_pk_bf16_f32 v61, v62, v63
	global_store_dwordx2 v[40:41], v[60:61], off offset:512
	v_cvt_pk_bf16_f32 v64, v64, v65
	v_cvt_pk_bf16_f32 v65, v66, v67
	global_store_dwordx2 v[40:41], v[64:65], off offset:1024
	v_cvt_pk_bf16_f32 v68, v68, v69
	v_cvt_pk_bf16_f32 v69, v70, v71
	global_store_dwordx2 v[40:41], v[68:69], off offset:1536
	s_waitcnt lgkmcnt(0)
	v_add_f32_e32 v19, v19, v20
	ds_bpermute_b32 v20, v13, v19
	s_waitcnt lgkmcnt(0)
	v_add_f32_e32 v19, v19, v20
	ds_bpermute_b32 v20, v15, v19
	s_waitcnt lgkmcnt(0)
	v_add_f32_e32 v19, v19, v20
	ds_bpermute_b32 v20, v16, v19
	s_waitcnt lgkmcnt(0)
	v_add_f32_e32 v19, v19, v20
	ds_bpermute_b32 v20, v17, v19
	s_waitcnt lgkmcnt(0)
	v_add_f32_e32 v19, v19, v20
	ds_bpermute_b32 v20, v18, v19
	v_lshl_add_u64 v[4:5], v[4:5], 0, s[8:9]
	s_and_saveexec_b64 s[14:15], s[4:5]
	s_waitcnt lgkmcnt(0)
	v_add_f32_e32 v19, v19, v20
	v_lshl_add_u64 v[20:21], v[6:7], 0, v[2:3]
	v_cndmask_b32_e64 v19, 0, v19, s[6:7]
	s_nop 0
	global_store_dword v[20:21], v19, off
	s_or_b64 exec, exec, s[14:15]
	v_lshl_add_u64 v[2:3], v[2:3], 0, s[2:3]
	v_lshl_add_u64 v[20:21], v[6:7], 0, v[4:5]
	v_add_co_u32_e32 v40, vcc, s16, v20
	s_nop 0
	v_addc_co_u32_e32 v41, vcc, 0, v21, vcc
	v_mul_f32_e32 v19, v77, v77
	v_fmac_f32_e32 v19, v76, v76
	v_mul_f32_e32 v20, v79, v79
	v_fmac_f32_e32 v20, v78, v78
	v_add_f32_e32 v19, v19, v20
	v_mul_f32_e32 v20, v81, v81
	v_mul_f32_e32 v21, v83, v83
	v_fmac_f32_e32 v20, v80, v80
	v_fmac_f32_e32 v21, v82, v82
	v_add_f32_e32 v20, v20, v21
	v_add_f32_e32 v19, v19, v20
	v_mul_f32_e32 v20, v85, v85
	v_mul_f32_e32 v21, v87, v87
	v_fmac_f32_e32 v20, v84, v84
	v_fmac_f32_e32 v21, v86, v86
	v_add_f32_e32 v20, v20, v21
	v_add_f32_e32 v19, v19, v20
	v_mul_f32_e32 v20, v89, v89
	v_mul_f32_e32 v21, v91, v91
	v_fmac_f32_e32 v20, v88, v88
	v_fmac_f32_e32 v21, v90, v90
	v_add_f32_e32 v20, v20, v21
	v_add_f32_e32 v19, v19, v20
	ds_bpermute_b32 v20, v12, v19
	v_cvt_pk_bf16_f32 v76, v76, v77
	v_cvt_pk_bf16_f32 v77, v78, v79
	global_store_dwordx2 v[40:41], v[76:77], off
	v_cvt_pk_bf16_f32 v80, v80, v81
	v_cvt_pk_bf16_f32 v81, v82, v83
	global_store_dwordx2 v[40:41], v[80:81], off offset:512
	v_cvt_pk_bf16_f32 v84, v84, v85
	v_cvt_pk_bf16_f32 v85, v86, v87
	global_store_dwordx2 v[40:41], v[84:85], off offset:1024
	v_cvt_pk_bf16_f32 v88, v88, v89
	v_cvt_pk_bf16_f32 v89, v90, v91
	global_store_dwordx2 v[40:41], v[88:89], off offset:1536
	s_waitcnt lgkmcnt(0)
	v_add_f32_e32 v19, v19, v20
	ds_bpermute_b32 v20, v13, v19
	s_waitcnt lgkmcnt(0)
	v_add_f32_e32 v19, v19, v20
	ds_bpermute_b32 v20, v15, v19
	s_waitcnt lgkmcnt(0)
	v_add_f32_e32 v19, v19, v20
	ds_bpermute_b32 v20, v16, v19
	s_waitcnt lgkmcnt(0)
	v_add_f32_e32 v19, v19, v20
	ds_bpermute_b32 v20, v17, v19
	s_waitcnt lgkmcnt(0)
	v_add_f32_e32 v19, v19, v20
	ds_bpermute_b32 v20, v18, v19
	v_lshl_add_u64 v[4:5], v[4:5], 0, s[8:9]
	s_and_saveexec_b64 s[14:15], s[4:5]
	s_waitcnt lgkmcnt(0)
	v_add_f32_e32 v19, v19, v20
	v_lshl_add_u64 v[20:21], v[6:7], 0, v[2:3]
	v_cndmask_b32_e64 v19, 0, v19, s[6:7]
	s_nop 0
	global_store_dword v[20:21], v19, off
	s_or_b64 exec, exec, s[14:15]
	v_lshl_add_u64 v[2:3], v[2:3], 0, s[2:3]
